# baseline (speedup 1.0000x reference)
; DI int tid_() { int t = threadIdx.x; asm volatile("" : "+v"(t)); return t; }
; DI int bid_() { int b = blockIdx.x; asm volatile("" : "+s"(b)); return b; }
; DI void phase_hg2(const Params& p, int L) {
;     ...
;   for (int idx = bid_() * 512 + tid_(); idx < ncombo * 16384; idx += gridDim.x * 512) {
;     const int combo = idx >> 14, e = idx & 16383, k = e >> 7; const int dir = (combo >> 3) & 1;
;     const long s_st = dir ? -16384 : 16384; const int s_pv = dir ? -128 : 128;
;     float* sp = ST + ((size_t)combo * nsc + (dir ? nsc - 1 : 0)) * 16384 + e;
;     const float* pp = PV + ((size_t)combo * nsc + (dir ? nsc - 1 : 0)) * 128 + k;
;     float carry = 0.f;
.LBB0_89:
	v_and_b32_e32 v0, 0x20000, v24
	v_cmp_eq_u32_e32 vcc, 0, v0
	v_mov_b32_e32 v0, 0xffffc000
	v_mov_b32_e32 v1, 0x4000
	v_cndmask_b32_e32 v22, v0, v1, vcc
	v_ashrrev_i32_e32 v0, 14, v24
	v_bfe_i32 v23, v24, 17, 1
	v_ashrrev_i32_e32 v1, 31, v0
	v_lshlrev_b64 v[0:1], s13, v[0:1]
	v_and_b32_e32 v96, s12, v23
	v_lshl_add_u64 v[0:1], v[0:1], 0, v[96:97]
	v_lshrrev_b16_e32 v8, 5, v25
	v_lshlrev_b64 v[2:3], 9, v[0:1]
	s_movk_i32 s2, 0x1fc
	v_and_b32_e32 v9, 0x3fff, v25
	v_lshlrev_b64 v[6:7], 16, v[0:1]
	v_and_or_b32 v2, v8, s2, v2
	s_mov_b64 s[42:43], 0x1ab40000
	v_mov_b32_e32 v0, 0xffffff80
	v_mov_b32_e32 v1, 0x80
	v_lshl_add_u64 v[2:3], v[2:3], 0, s[42:43]
	v_lshl_or_b32 v6, v9, 2, v6
	s_mov_b64 s[42:43], 0x18b40000
	v_cndmask_b32_e32 v4, v0, v1, vcc
	v_mov_b32_e32 v5, v23
	v_lshl_add_u64 v[6:7], v[6:7], 0, s[42:43]
	s_mov_b32 s40, 0
	v_lshlrev_b64 v[0:1], 2, v[4:5]
	v_lshlrev_b64 v[4:5], 5, v[4:5]
	v_lshlrev_b64 v[8:9], 5, v[22:23]
	v_lshl_add_u64 v[10:11], v[22:23], 3, v[6:7]
	v_mad_i64_i32 v[12:13], s[42:43], v22, 12, v[6:7]
	v_lshl_add_u64 v[14:15], v[22:23], 4, v[6:7]
	v_mad_i64_i32 v[16:17], s[42:43], v22, 20, v[6:7]
	v_mad_i64_i32 v[18:19], s[42:43], v22, 24, v[6:7]
	v_mad_i64_i32 v[20:21], s[42:43], v22, 28, v[6:7]
	v_lshl_add_u64 v[22:23], v[22:23], 2, v[6:7]
	v_mov_b32_e32 v26, 0
	v_add_u32_e32 v124, s58, v24
	v_add_u16_e32 v125, s58, v25
	v_mov_b32_e32 v161, 0
	v_and_b32_e32 v100, 0x20000, v124
	v_cmp_eq_u32_e32 vcc, 0, v100
	v_mov_b32_e32 v100, 0xffffc000
	v_mov_b32_e32 v101, 0x4000
	v_cndmask_b32_e32 v122, v100, v101, vcc
	v_ashrrev_i32_e32 v100, 14, v124
	v_bfe_i32 v123, v124, 17, 1
	v_ashrrev_i32_e32 v101, 31, v100
	v_lshlrev_b64 v[100:101], s13, v[100:101]
	v_and_b32_e32 v160, s12, v123
	v_lshl_add_u64 v[100:101], v[100:101], 0, v[160:161]
	v_lshrrev_b16_e32 v108, 5, v125
	v_lshlrev_b64 v[102:103], 9, v[100:101]
	s_movk_i32 s2, 0x1fc
	v_and_b32_e32 v109, 0x3fff, v125
	v_lshlrev_b64 v[106:107], 16, v[100:101]
	v_and_or_b32 v102, v108, s2, v102
	s_mov_b64 s[42:43], 0x1ab40000
	v_mov_b32_e32 v100, 0xffffff80
	v_mov_b32_e32 v101, 0x80
	v_lshl_add_u64 v[102:103], v[102:103], 0, s[42:43]
	v_lshl_or_b32 v106, v109, 2, v106
	s_mov_b64 s[42:43], 0x18b40000
	v_cndmask_b32_e32 v104, v100, v101, vcc
	v_mov_b32_e32 v105, v123
	v_lshl_add_u64 v[106:107], v[106:107], 0, s[42:43]
	s_mov_b32 s40, 0
	v_lshlrev_b64 v[100:101], 2, v[104:105]
	v_lshlrev_b64 v[104:105], 5, v[104:105]
	v_lshlrev_b64 v[108:109], 5, v[122:123]
	v_lshl_add_u64 v[110:111], v[122:123], 3, v[106:107]
	v_mad_i64_i32 v[112:113], s[42:43], v122, 12, v[106:107]
	v_lshl_add_u64 v[114:115], v[122:123], 4, v[106:107]
	v_mad_i64_i32 v[116:117], s[42:43], v122, 20, v[106:107]
	v_mad_i64_i32 v[118:119], s[42:43], v122, 24, v[106:107]
	v_mad_i64_i32 v[120:121], s[42:43], v122, 28, v[106:107]
	v_lshl_add_u64 v[122:123], v[122:123], 2, v[106:107]
	v_mov_b32_e32 v126, 0
; DI int tid_() { int t = threadIdx.x; asm volatile("" : "+v"(t)); return t; }
; DI int bid_() { int b = blockIdx.x; asm volatile("" : "+s"(b)); return b; }
; DI void phase_hg2(const Params& p, int L) {
;     ...
;   for (int idx = bid_() * 512 + tid_(); idx < ncombo * 16384; idx += gridDim.x * 512) {
;     const int combo = idx >> 14, e = idx & 16383, k = e >> 7; const int dir = (combo >> 3) & 1;
;     const long s_st = dir ? -16384 : 16384; const int s_pv = dir ? -128 : 128;
;     float* sp = ST + ((size_t)combo * nsc + (dir ? nsc - 1 : 0)) * 16384 + e;
;     const float* pp = PV + ((size_t)combo * nsc + (dir ? nsc - 1 : 0)) * 128 + k;
;     float carry = 0.f;
;     for (int j0 = 0; j0 < nsc; j0 += 8) {
;       float tmp[8], pv[8];
; #pragma unroll
;       for (int u = 0; u < 8; ++u) { tmp[u] = sp[u * s_st]; pv[u] = pp[u * s_pv]; }
; #pragma unroll
;       for (int u = 0; u < 8; ++u) { sp[u * s_st] = carry; carry = pv[u] * carry + tmp[u]; }
;       sp += 8 * s_st; pp += 8 * s_pv;
;     }
;   }
.LBB0_90:
	v_lshl_add_u64 v[28:29], s[26:27], 0, v[2:3]
	v_lshl_add_u64 v[30:31], s[26:27], 0, v[6:7]
	global_load_dword v27, v[30:31], off
	global_load_dword v46, v[28:29], off
	v_lshl_add_u64 v[32:33], s[26:27], 0, v[22:23]
	v_lshl_add_u64 v[28:29], v[28:29], 0, v[0:1]
	global_load_dword v47, v[32:33], off
	global_load_dword v48, v[28:29], off
	v_lshl_add_u64 v[34:35], s[26:27], 0, v[10:11]
	v_lshl_add_u64 v[28:29], v[28:29], 0, v[0:1]
	global_load_dword v49, v[34:35], off
	global_load_dword v50, v[28:29], off
	v_lshl_add_u64 v[36:37], s[26:27], 0, v[12:13]
	v_lshl_add_u64 v[28:29], v[28:29], 0, v[0:1]
	global_load_dword v51, v[36:37], off
	global_load_dword v52, v[28:29], off
	v_lshl_add_u64 v[38:39], s[26:27], 0, v[14:15]
	v_lshl_add_u64 v[28:29], v[28:29], 0, v[0:1]
	global_load_dword v53, v[38:39], off
	global_load_dword v54, v[28:29], off
	v_lshl_add_u64 v[40:41], s[26:27], 0, v[16:17]
	v_lshl_add_u64 v[28:29], v[28:29], 0, v[0:1]
	global_load_dword v55, v[40:41], off
	global_load_dword v56, v[28:29], off
	v_lshl_add_u64 v[42:43], s[26:27], 0, v[18:19]
	v_lshl_add_u64 v[28:29], v[28:29], 0, v[0:1]
	global_load_dword v57, v[42:43], off
	global_load_dword v58, v[28:29], off
	v_lshl_add_u64 v[44:45], s[26:27], 0, v[20:21]
	v_lshl_add_u64 v[28:29], v[28:29], 0, v[0:1]
	global_load_dword v59, v[44:45], off
	s_add_i32 s40, s40, 8
	global_load_dword v28, v[28:29], off
	v_lshl_add_u64 v[128:129], s[26:27], 0, v[102:103]
	v_lshl_add_u64 v[130:131], s[26:27], 0, v[106:107]
	global_load_dword v127, v[130:131], off
	global_load_dword v146, v[128:129], off
	v_lshl_add_u64 v[132:133], s[26:27], 0, v[122:123]
	v_lshl_add_u64 v[128:129], v[128:129], 0, v[100:101]
	global_load_dword v147, v[132:133], off
	global_load_dword v148, v[128:129], off
	v_lshl_add_u64 v[134:135], s[26:27], 0, v[110:111]
	v_lshl_add_u64 v[128:129], v[128:129], 0, v[100:101]
	global_load_dword v149, v[134:135], off
	global_load_dword v150, v[128:129], off
	v_lshl_add_u64 v[136:137], s[26:27], 0, v[112:113]
	v_lshl_add_u64 v[128:129], v[128:129], 0, v[100:101]
	global_load_dword v151, v[136:137], off
	global_load_dword v152, v[128:129], off
	v_lshl_add_u64 v[138:139], s[26:27], 0, v[114:115]
	v_lshl_add_u64 v[128:129], v[128:129], 0, v[100:101]
	global_load_dword v153, v[138:139], off
	global_load_dword v154, v[128:129], off
	v_lshl_add_u64 v[140:141], s[26:27], 0, v[116:117]
	v_lshl_add_u64 v[128:129], v[128:129], 0, v[100:101]
	global_load_dword v155, v[140:141], off
	global_load_dword v156, v[128:129], off
	v_lshl_add_u64 v[142:143], s[26:27], 0, v[118:119]
	v_lshl_add_u64 v[128:129], v[128:129], 0, v[100:101]
	global_load_dword v157, v[142:143], off
	global_load_dword v158, v[128:129], off
	v_lshl_add_u64 v[144:145], s[26:27], 0, v[120:121]
	v_lshl_add_u64 v[128:129], v[128:129], 0, v[100:101]
	global_load_dword v159, v[144:145], off
	global_load_dword v128, v[128:129], off
	v_lshl_add_u64 v[2:3], v[2:3], 0, v[4:5]
	global_store_dword v[30:31], v26, off
	v_lshl_add_u64 v[6:7], v[6:7], 0, v[8:9]
	v_lshl_add_u64 v[10:11], v[10:11], 0, v[8:9]
	v_lshl_add_u64 v[12:13], v[12:13], 0, v[8:9]
	v_lshl_add_u64 v[14:15], v[14:15], 0, v[8:9]
	v_lshl_add_u64 v[16:17], v[16:17], 0, v[8:9]
	v_lshl_add_u64 v[18:19], v[18:19], 0, v[8:9]
	v_lshl_add_u64 v[20:21], v[20:21], 0, v[8:9]
	v_lshl_add_u64 v[22:23], v[22:23], 0, v[8:9]
	s_waitcnt vmcnt(31)
	v_fmac_f32_e32 v27, v26, v46
	global_store_dword v[32:33], v27, off
	s_waitcnt vmcnt(30)
	v_fmac_f32_e32 v47, v27, v48
	global_store_dword v[34:35], v47, off
	s_waitcnt vmcnt(29)
	v_fmac_f32_e32 v49, v47, v50
	global_store_dword v[36:37], v49, off
	s_waitcnt vmcnt(28)
	v_fmac_f32_e32 v51, v49, v52
	global_store_dword v[38:39], v51, off
	s_waitcnt vmcnt(27)
	v_fmac_f32_e32 v53, v51, v54
	global_store_dword v[40:41], v53, off
	s_waitcnt vmcnt(26)
	v_fmac_f32_e32 v55, v53, v56
	global_store_dword v[42:43], v55, off
	s_waitcnt vmcnt(25)
	v_fmac_f32_e32 v57, v55, v58
	global_store_dword v[44:45], v57, off
	s_waitcnt vmcnt(24)
	v_fmac_f32_e32 v59, v57, v28
	v_mov_b32_e32 v26, v59
	v_lshl_add_u64 v[102:103], v[102:103], 0, v[104:105]
	global_store_dword v[130:131], v126, off
	v_lshl_add_u64 v[106:107], v[106:107], 0, v[108:109]
	v_lshl_add_u64 v[110:111], v[110:111], 0, v[108:109]
	v_lshl_add_u64 v[112:113], v[112:113], 0, v[108:109]
	v_lshl_add_u64 v[114:115], v[114:115], 0, v[108:109]
	v_lshl_add_u64 v[116:117], v[116:117], 0, v[108:109]
	v_lshl_add_u64 v[118:119], v[118:119], 0, v[108:109]
	v_lshl_add_u64 v[120:121], v[120:121], 0, v[108:109]
	v_lshl_add_u64 v[122:123], v[122:123], 0, v[108:109]
	s_waitcnt vmcnt(23)
	v_fmac_f32_e32 v127, v126, v146
	global_store_dword v[132:133], v127, off
	s_waitcnt vmcnt(22)
	v_fmac_f32_e32 v147, v127, v148
	global_store_dword v[134:135], v147, off
	s_waitcnt vmcnt(21)
	v_fmac_f32_e32 v149, v147, v150
	global_store_dword v[136:137], v149, off
	s_waitcnt vmcnt(20)
	v_fmac_f32_e32 v151, v149, v152
	global_store_dword v[138:139], v151, off
	s_waitcnt vmcnt(19)
	v_fmac_f32_e32 v153, v151, v154
	global_store_dword v[140:141], v153, off
	s_waitcnt vmcnt(18)
	v_fmac_f32_e32 v155, v153, v156
	global_store_dword v[142:143], v155, off
	s_waitcnt vmcnt(17)
	v_fmac_f32_e32 v157, v155, v158
	global_store_dword v[144:145], v157, off
	s_waitcnt vmcnt(16)
	v_fmac_f32_e32 v159, v157, v128
	v_mov_b32_e32 v126, v159
	s_cmp_lt_u32 s40, s7
	s_cbranch_scc1 .LBB0_90
	v_add_u32_e32 v24, s58, v24
	v_add_u16_e32 v25, s58, v25
	v_add_u32_e32 v24, s58, v24
	v_cmp_le_i32_e32 vcc, s6, v24
	s_or_b64 s[38:39], vcc, s[38:39]
	v_add_u16_e32 v25, s58, v25
	s_andn2_b64 exec, exec, s[38:39]
	s_cbranch_execnz .LBB0_89
